# younger-half priority raise (waves 4-7) extended to the DOWN tail item loop
# baseline (speedup 1.0000x reference)
; template <int MODE, int EPI, int BN>
; DI void gemm_phase(CP p, const GArgs& g, int NT, char* smem) {
;     ...
;   const int ntail = NT * (BN / 64);
;   for (int e = (int)gridDim.x - 1 - (int)blockIdx.x; e < ntail; e += gridDim.x) gemm_tile<MODE, EPI, 64>(p, g, NMT - 1, e, smem);
.LBB0_1285:
	v_readfirstlane_b32 s98, v179
	s_nop 3
	s_lshr_b32 s98, s98, 6
	s_cmp_ge_u32 s98, 4
	s_cbranch_scc0 .Ldtail_prio
	s_setprio 1

; DI void conv_mix(CP p, int l, int t, char* smem) {
;   CJob jb;
;   if (t < 592) jb = CJob{p.w_in + (size_t)l * 1024 * 2368, p.mix_norm + l * 1024, p.wM + OFF_IN, 1024, 2368, 1024, 3, 16};
;   else if (t < 640) { t -= 592; jb = CJob{p.w_uq + (size_t)l * 256 * 768, p.q_norm + l * 256, p.wM + OFF_UQ, 256, 768, 256, 0, 4}; }
;   else if (t < 672) { t -= 640; jb = CJob{p.w_ukv + (size_t)l * 128 * 1024, p.kv_norm + l * 128, p.wM + OFF_UKV, 128, 1024, 128, 0, 2}; }
;   else if (t < 688) { t -= 672; int d = t >> 3; t &= 7; jb = CJob{p.decay_w2 + (size_t)(l * 2 + d) * 64 * 512, nullptr, p.wM + OFF_DEC + d * 32768, 64, 512, 64, 0, 1}; }
;   else if (t < 704) { t -= 688; int d = t >> 3; t &= 7; jb = CJob{p.iclr_a2 + (size_t)(l * 2 + d) * 64 * 512, nullptr, p.wM + OFF_A + d * 32768, 64, 512, 64, 0, 1}; }
;   else if (t < 728) { t -= 704; jb = CJob{p.gate_g2 + (size_t)l * 160 * 512, nullptr, p.wM + OFF_G, 160, 512, 192, 0, 3}; }
;   else if (t < 984) { t -= 728; jb = CJob{p.w_out + (size_t)l * 1024 * 1024, nullptr, p.wM + OFF_OUT, 1024, 1024, 1024, 0, 16}; }
; DI void run_phase(CP p, int ph, char* smem) {
;     ...
;       gemm_phase<0, EPI_RES, 256>(p, g, 4, smem);
;       if (layer == 0 && fidx >= 0) for (int it = fidx; it < NCONV_MIX; it += nfill) conv_mix(p, k == 1 ? 0 : 1, it, smem);
.LBB0_1300:
	s_setprio 0
	v_readlane_b32 s2, v253, 23
	v_readlane_b32 s8, v252, 44
	v_readlane_b32 s3, v253, 24
	v_readlane_b32 s9, v252, 45
	s_or_b64 s[2:3], s[8:9], s[2:3]
	s_and_b64 vcc, exec, s[2:3]
	s_cbranch_vccnz .LBB0_1357
	s_load_dwordx2 s[8:9], s[0:1], 0xc0
	s_load_dwordx2 s[2:3], s[0:1], 0x120
	s_and_b64 s[10:11], s[48:49], exec
	s_cselect_b32 s10, 0, 0x400000
	s_load_dwordx4 s[44:47], s[0:1], 0x88
	s_waitcnt lgkmcnt(0)
	s_add_u32 s8, s8, s10
	s_addc_u32 s9, s9, 0
	s_add_u32 s10, s2, 0x610000
	s_addc_u32 s11, s3, 0
	s_and_b64 s[14:15], s[48:49], exec
	s_cselect_b32 s16, 0, 0x50000
	s_load_dwordx2 s[14:15], s[0:1], 0x78
	s_add_u32 s16, s46, s16
	s_addc_u32 s17, s47, 0
	s_add_u32 s42, s2, 0x5e0000
	s_addc_u32 s43, s3, 0
	s_and_b64 s[40:41], s[48:49], exec
	s_cselect_b32 s75, 0, 2
	s_add_u32 s80, s2, 0x5c0000
	s_addc_u32 s81, s3, 0
	s_load_dwordx8 s[56:63], s[0:1], 0x50
	s_add_u32 s82, s2, 0x5a0000
	s_addc_u32 s83, s3, 0
	s_and_b64 s[40:41], s[48:49], exec
	s_cselect_b32 s40, 0, 0x80000
	s_waitcnt lgkmcnt(0)
	s_add_u32 s46, s62, s40
	s_addc_u32 s47, s63, 0
	s_and_b64 s[40:41], s[48:49], exec
	s_cselect_b32 s40, 0, 0x200
	s_add_u32 s50, s60, s40
	s_addc_u32 s51, s61, 0
	s_add_u32 s52, s2, 0x560000
	s_addc_u32 s53, s3, 0
	s_and_b64 s[40:41], s[48:49], exec
	s_cselect_b32 s40, 0, 0xc0000
	s_add_u32 s54, s58, s40
	s_addc_u32 s55, s59, 0
	s_and_b64 s[40:41], s[48:49], exec
	s_cselect_b32 s40, 0, 0x400
	s_add_u32 s56, s56, s40
	s_load_dwordx4 s[64:67], s[0:1], 0x38
	s_addc_u32 s57, s57, 0
	s_add_u32 s58, s2, 0x500000
	s_addc_u32 s59, s3, 0
	s_and_b64 s[40:41], s[48:49], exec
	s_cselect_b32 s40, 0, 0x940000
	s_waitcnt lgkmcnt(0)
	s_add_u32 s60, s66, s40
	s_addc_u32 s61, s67, 0
	s_and_b64 s[40:41], s[48:49], exec
	s_cselect_b32 s40, 0, 0x1000
	s_add_u32 s48, s64, s40
	s_addc_u32 s49, s65, 0
	v_readlane_b32 s92, v253, 5
	s_branch .LBB0_1305
